# phase G fused epilogue: residual quads of all 8 row groups prefetched up front with counted waits instead of a load-wait round trip per group
# speedup vs baseline: 1.0143x; 1.0092x over previous
; __device__ __forceinline__ f32x4 unpack4(u32x2 w) { return (f32x4){bflo(w.x), bfhi(w.x), bflo(w.y), bfhi(w.y)}; }
; __device__ __forceinline__ int lane_fresh() { int l; asm volatile("v_mbcnt_lo_u32_b32 %0, -1, 0\n\tv_mbcnt_hi_u32_b32 %0, -1, %0" : "=v"(l)); return l; }
; __device__ __forceinline__ float shfl_xor_f(float v, int mask) { const int l = lane_fresh(); return __int_as_float(__builtin_amdgcn_ds_bpermute((l ^ mask) << 2, __float_as_int(v))); }
; __device__ __forceinline__ void load_pair16(const u16* rowp32, int fq, u32x2& a, u32x2& b) {
;   const u32x4 w = *(const u32x4*)(rowp32 + ((fq & 1) * 16 + (fq >> 1) * 8));
;   auto rx = __builtin_amdgcn_permlane16_swap(w.x, w.z, false, false);
;   auto ry = __builtin_amdgcn_permlane16_swap(w.y, w.w, false, false);
;   a = (u32x2){rx[0], ry[0]}; b = (u32x2){rx[1], ry[1]};
; }
; __device__ __forceinline__ void phaseG(const Params& p, const int wv, const int rep, unsigned* bar, const bool fused) {
;     ...
;         const int lane_e = lane_fresh(), fr = lane_e & 15, fq = lane_e >> 4;
; #pragma unroll
;         for (int ai = 0; ai < 2; ++ai)
; #pragma unroll
;           for (int m = 0; m < 4; ++m) {
;             const int rrow = ai * 128 + wr * 64 + m * 16 + fr;
;             float ss = 0.f;
; #pragma unroll
;             for (int bj = 0; bj < 2; ++bj) {
;               u32x2 hp[2];
;               load_pair16(H2 + (size_t)(brow + rrow) * 1024 + bcol + bj * 128 + wc * 32, fq, hp[0], hp[1]);
; #pragma unroll
;               for (int n = 0; n < 2; ++n) {
;                 f32x4 v = acc[ai][bj][m][n] + unpack4(hp[n]);
;                 acc[ai][bj][m][n] = v;
;                 ss += v[0] * v[0] + v[1] * v[1] + v[2] * v[2] + v[3] * v[3];
;               }
;             }
;             ss += shfl_xor_f(ss, 16); ss += shfl_xor_f(ss, 32);
;             if (fq == 0) red[rrow * 4 + wc] = ss;
;           }
.LBB0_1144:
	s_andn2_b64 vcc, exec, s[4:5]
	s_cbranch_vccnz .LBB0_1135
	v_mbcnt_lo_u32_b32 v143, -1, 0
	v_mbcnt_hi_u32_b32 v143, -1, v143
	s_lshl_b32 s4, s86, 1
	v_ashrrev_i32_e32 v130, 2, v143
	v_and_b32_e32 v128, 16, v143
	v_and_b32_e32 v130, -8, v130
	v_and_or_b32 v142, v143, 15, s65
	s_add_u32 s4, s75, s4
	v_add_u32_e32 v130, v130, v128
	s_addc_u32 s5, s76, 0
	v_ashrrev_i32_e32 v131, 31, v130
	v_add_u32_e32 v128, s87, v142
	v_lshl_add_u64 v[138:139], v[130:131], 1, s[4:5]
	v_lshlrev_b64 v[130:131], 11, v[128:129]
	v_lshl_add_u64 v[134:135], v[138:139], 0, v[130:131]
	v_mov_b32_e32 v157, 0
	v_mov_b32_e32 v156, v128
	v_lshlrev_b64 v[158:159], 11, v[156:157]
	v_lshl_add_u64 v[158:159], v[138:139], 0, v[158:159]
	global_load_dwordx4 v[160:163], v[158:159], off
	global_load_dwordx4 v[164:167], v[158:159], off offset:256
	v_add_u32_e32 v156, 0x10, v128
	v_lshlrev_b64 v[158:159], 11, v[156:157]
	v_lshl_add_u64 v[158:159], v[138:139], 0, v[158:159]
	global_load_dwordx4 v[168:171], v[158:159], off
	global_load_dwordx4 v[172:175], v[158:159], off offset:256
	v_add_u32_e32 v156, 0x20, v128
	v_lshlrev_b64 v[158:159], 11, v[156:157]
	v_lshl_add_u64 v[158:159], v[138:139], 0, v[158:159]
	global_load_dwordx4 v[176:179], v[158:159], off
	global_load_dwordx4 v[180:183], v[158:159], off offset:256
	v_add_u32_e32 v156, 0x30, v128
	v_lshlrev_b64 v[158:159], 11, v[156:157]
	v_lshl_add_u64 v[158:159], v[138:139], 0, v[158:159]
	global_load_dwordx4 v[184:187], v[158:159], off
	global_load_dwordx4 v[188:191], v[158:159], off offset:256
	v_add_u32_e32 v156, 0x80, v128
	v_lshlrev_b64 v[158:159], 11, v[156:157]
	v_lshl_add_u64 v[158:159], v[138:139], 0, v[158:159]
	global_load_dwordx4 v[192:195], v[158:159], off
	global_load_dwordx4 v[196:199], v[158:159], off offset:256
	v_add_u32_e32 v156, 0x90, v128
	v_lshlrev_b64 v[158:159], 11, v[156:157]
	v_lshl_add_u64 v[158:159], v[138:139], 0, v[158:159]
	global_load_dwordx4 v[200:203], v[158:159], off
	global_load_dwordx4 v[204:207], v[158:159], off offset:256
	v_add_u32_e32 v156, 0xa0, v128
	v_lshlrev_b64 v[158:159], 11, v[156:157]
	v_lshl_add_u64 v[158:159], v[138:139], 0, v[158:159]
	global_load_dwordx4 v[208:211], v[158:159], off
	global_load_dwordx4 v[212:215], v[158:159], off offset:256
	v_add_u32_e32 v156, 0xb0, v128
	v_lshlrev_b64 v[158:159], 11, v[156:157]
	v_lshl_add_u64 v[158:159], v[138:139], 0, v[158:159]
	global_load_dwordx4 v[216:219], v[158:159], off
	global_load_dwordx4 v[220:223], v[158:159], off offset:256
	s_waitcnt vmcnt(14)
	v_mov_b32_e32 v130, v160
	v_mov_b32_e32 v131, v161
	v_mov_b32_e32 v132, v162
	v_mov_b32_e32 v133, v163
	s_nop 0
	v_mov_b32_e32 v134, v164
	v_mov_b32_e32 v135, v165
	v_mov_b32_e32 v136, v166
	v_mov_b32_e32 v137, v167
	v_mbcnt_lo_u32_b32 v128, -1, 0
	v_mbcnt_hi_u32_b32 v128, -1, v128
	v_cmp_gt_u32_e32 vcc, 16, v143
	v_lshlrev_b32_e32 v128, 2, v128
	v_xor_b32_e32 v128, 64, v128
	v_mov_b32_e32 v145, v132
	v_mov_b32_e32 v147, v133
	s_nop 0
	v_permlane16_swap_b32_e32 v130, v145
	v_permlane16_swap_b32_e32 v131, v147
	v_permlane16_swap_b32_e32 v134, v136
	v_permlane16_swap_b32_e32 v135, v137
	v_lshlrev_b32_e32 v132, 16, v130
	v_and_b32_e32 v133, 0xffff0000, v130
	v_lshlrev_b32_e32 v144, 16, v145
	v_and_b32_e32 v145, 0xffff0000, v145
	v_lshlrev_b32_e32 v130, 16, v131
	v_and_b32_e32 v131, 0xffff0000, v131
	v_lshlrev_b32_e32 v146, 16, v147
	v_and_b32_e32 v147, 0xffff0000, v147
	v_lshlrev_b32_e32 v148, 16, v134
	v_and_b32_e32 v149, 0xffff0000, v134
	v_lshlrev_b32_e32 v152, 16, v136
	v_and_b32_e32 v153, 0xffff0000, v136
	v_lshlrev_b32_e32 v154, 16, v137
	v_and_b32_e32 v155, 0xffff0000, v137
	v_pk_add_f32 v[136:137], v[112:113], v[132:133]
	v_pk_add_f32 v[132:133], v[116:117], v[144:145]
	v_lshlrev_b32_e32 v150, 16, v135
	v_and_b32_e32 v151, 0xffff0000, v135
	v_pk_add_f32 v[134:135], v[114:115], v[130:131]
	v_pk_add_f32 v[130:131], v[118:119], v[146:147]
	v_pk_add_f32 v[118:119], v[120:121], v[148:149]
	v_mul_f32_e32 v120, v137, v137
	v_mul_f32_e32 v121, v133, v133
	v_pk_add_f32 v[116:117], v[122:123], v[150:151]
	v_pk_add_f32 v[114:115], v[124:125], v[152:153]
	v_mul_f32_e32 v122, v119, v119
	v_fmac_f32_e32 v120, v136, v136
	v_fmac_f32_e32 v121, v132, v132
	v_mul_f32_e32 v123, v115, v115
	v_fmac_f32_e32 v122, v118, v118
	v_fmac_f32_e32 v120, v134, v134
	v_fmac_f32_e32 v121, v130, v130
	v_pk_add_f32 v[112:113], v[126:127], v[154:155]
	v_fmac_f32_e32 v123, v114, v114
	v_fmac_f32_e32 v122, v116, v116
	v_fmac_f32_e32 v120, v135, v135
	v_fmac_f32_e32 v121, v131, v131
	v_fmac_f32_e32 v123, v112, v112
	v_fmac_f32_e32 v122, v117, v117
	v_add_f32_e32 v120, v120, v121
	v_fmac_f32_e32 v123, v113, v113
	v_add_f32_e32 v120, v120, v122
	v_add_f32_e32 v120, v123, v120
	ds_bpermute_b32 v121, v128, v120
	v_mbcnt_lo_u32_b32 v122, -1, 0
	v_mbcnt_hi_u32_b32 v122, -1, v122
	s_waitcnt lgkmcnt(0)
	v_add_f32_e32 v120, v120, v121
	v_lshlrev_b32_e32 v122, 2, v122
	v_xor_b32_e32 v121, 0x80, v122
	ds_bpermute_b32 v121, v121, v120
	s_and_saveexec_b64 s[4:5], vcc
	s_cbranch_execz .LBB0_1147
	s_waitcnt lgkmcnt(0)
	v_add_f32_e32 v120, v120, v121
	v_lshl_add_u32 v121, v142, 4, s77
	ds_write_b32 v121, v120
; __device__ __forceinline__ f32x4 unpack4(u32x2 w) { return (f32x4){bflo(w.x), bfhi(w.x), bflo(w.y), bfhi(w.y)}; }
; __device__ __forceinline__ int lane_fresh() { int l; asm volatile("v_mbcnt_lo_u32_b32 %0, -1, 0\n\tv_mbcnt_hi_u32_b32 %0, -1, %0" : "=v"(l)); return l; }
; __device__ __forceinline__ float shfl_xor_f(float v, int mask) { const int l = lane_fresh(); return __int_as_float(__builtin_amdgcn_ds_bpermute((l ^ mask) << 2, __float_as_int(v))); }
; __device__ __forceinline__ void load_pair16(const u16* rowp32, int fq, u32x2& a, u32x2& b) {
;   const u32x4 w = *(const u32x4*)(rowp32 + ((fq & 1) * 16 + (fq >> 1) * 8));
;   auto rx = __builtin_amdgcn_permlane16_swap(w.x, w.z, false, false);
;   auto ry = __builtin_amdgcn_permlane16_swap(w.y, w.w, false, false);
;   a = (u32x2){rx[0], ry[0]}; b = (u32x2){rx[1], ry[1]};
; }
; __device__ __forceinline__ void phaseG(const Params& p, const int wv, const int rep, unsigned* bar, const bool fused) {
;     ...
;         const int lane_e = lane_fresh(), fr = lane_e & 15, fq = lane_e >> 4;
; #pragma unroll
;         for (int ai = 0; ai < 2; ++ai)
; #pragma unroll
;           for (int m = 0; m < 4; ++m) {
;             const int rrow = ai * 128 + wr * 64 + m * 16 + fr;
;             float ss = 0.f;
; #pragma unroll
;             for (int bj = 0; bj < 2; ++bj) {
;               u32x2 hp[2];
;               load_pair16(H2 + (size_t)(brow + rrow) * 1024 + bcol + bj * 128 + wc * 32, fq, hp[0], hp[1]);
; #pragma unroll
;               for (int n = 0; n < 2; ++n) {
;                 f32x4 v = acc[ai][bj][m][n] + unpack4(hp[n]);
;                 acc[ai][bj][m][n] = v;
;                 ss += v[0] * v[0] + v[1] * v[1] + v[2] * v[2] + v[3] * v[3];
;               }
;             }
;             ss += shfl_xor_f(ss, 16); ss += shfl_xor_f(ss, 32);
;             if (fq == 0) red[rrow * 4 + wc] = ss;
;           }
.LBB0_1147:
	s_or_b64 exec, exec, s[4:5]
	v_or_b32_e32 v143, 16, v142
	v_add_u32_e32 v128, s87, v143
	s_waitcnt lgkmcnt(0)
	v_lshlrev_b64 v[120:121], 11, v[128:129]
	v_lshl_add_u64 v[124:125], v[138:139], 0, v[120:121]
	s_waitcnt vmcnt(12)
	v_mov_b32_e32 v120, v168
	v_mov_b32_e32 v121, v169
	v_mov_b32_e32 v122, v170
	v_mov_b32_e32 v123, v171
	s_nop 0
	v_mov_b32_e32 v124, v172
	v_mov_b32_e32 v125, v173
	v_mov_b32_e32 v126, v174
	v_mov_b32_e32 v127, v175
	v_mbcnt_lo_u32_b32 v128, -1, 0
	v_mbcnt_hi_u32_b32 v128, -1, v128
	v_mov_b32_e32 v145, v122
	v_mov_b32_e32 v147, v123
	s_nop 0
	v_permlane16_swap_b32_e32 v120, v145
	v_permlane16_swap_b32_e32 v121, v147
	v_permlane16_swap_b32_e32 v124, v126
	v_permlane16_swap_b32_e32 v125, v127
	v_lshlrev_b32_e32 v122, 16, v120
	v_and_b32_e32 v123, 0xffff0000, v120
	v_lshlrev_b32_e32 v144, 16, v145
	v_and_b32_e32 v145, 0xffff0000, v145
	v_lshlrev_b32_e32 v120, 16, v121
	v_and_b32_e32 v121, 0xffff0000, v121
	v_lshlrev_b32_e32 v146, 16, v147
	v_and_b32_e32 v147, 0xffff0000, v147
	v_lshlrev_b32_e32 v148, 16, v124
	v_and_b32_e32 v149, 0xffff0000, v124
	v_lshlrev_b32_e32 v152, 16, v126
	v_and_b32_e32 v153, 0xffff0000, v126
	v_lshlrev_b32_e32 v154, 16, v127
	v_and_b32_e32 v155, 0xffff0000, v127
	v_pk_add_f32 v[126:127], v[96:97], v[122:123]
	v_pk_add_f32 v[122:123], v[100:101], v[144:145]
	v_lshlrev_b32_e32 v150, 16, v125
	v_and_b32_e32 v151, 0xffff0000, v125
	v_pk_add_f32 v[124:125], v[98:99], v[120:121]
	v_pk_add_f32 v[120:121], v[102:103], v[146:147]
	v_pk_add_f32 v[102:103], v[104:105], v[148:149]
	v_mul_f32_e32 v104, v127, v127
	v_mul_f32_e32 v105, v123, v123
	v_pk_add_f32 v[100:101], v[106:107], v[150:151]
	v_pk_add_f32 v[98:99], v[108:109], v[152:153]
	v_mul_f32_e32 v106, v103, v103
	v_fmac_f32_e32 v104, v126, v126
	v_fmac_f32_e32 v105, v122, v122
	v_mul_f32_e32 v107, v99, v99
	v_fmac_f32_e32 v106, v102, v102
	v_fmac_f32_e32 v104, v124, v124
	v_fmac_f32_e32 v105, v120, v120
	v_pk_add_f32 v[96:97], v[110:111], v[154:155]
	v_fmac_f32_e32 v107, v98, v98
	v_fmac_f32_e32 v106, v100, v100
	v_fmac_f32_e32 v104, v125, v125
	v_fmac_f32_e32 v105, v121, v121
	v_fmac_f32_e32 v107, v96, v96
	v_fmac_f32_e32 v106, v101, v101
	v_add_f32_e32 v104, v104, v105
	v_lshlrev_b32_e32 v128, 2, v128
	v_fmac_f32_e32 v107, v97, v97
	v_add_f32_e32 v104, v104, v106
	v_xor_b32_e32 v128, 64, v128
	v_add_f32_e32 v104, v107, v104
	ds_bpermute_b32 v105, v128, v104
	v_mbcnt_lo_u32_b32 v106, -1, 0
	v_mbcnt_hi_u32_b32 v106, -1, v106
	s_waitcnt lgkmcnt(0)
	v_add_f32_e32 v104, v104, v105
	v_lshlrev_b32_e32 v106, 2, v106
	v_xor_b32_e32 v105, 0x80, v106
	ds_bpermute_b32 v105, v105, v104
	s_and_saveexec_b64 s[4:5], vcc
	s_cbranch_execz .LBB0_1149
	s_waitcnt lgkmcnt(0)
	v_add_f32_e32 v104, v104, v105
	v_lshl_add_u32 v105, v143, 4, s77
	ds_write_b32 v105, v104
.LBB0_1149:
	s_or_b64 exec, exec, s[4:5]
	v_or_b32_e32 v143, 32, v142
	v_add_u32_e32 v128, s87, v143
	s_waitcnt lgkmcnt(0)
	v_lshlrev_b64 v[104:105], 11, v[128:129]
	v_lshl_add_u64 v[108:109], v[138:139], 0, v[104:105]
	s_waitcnt vmcnt(10)
	v_mov_b32_e32 v104, v176
	v_mov_b32_e32 v105, v177
	v_mov_b32_e32 v106, v178
	v_mov_b32_e32 v107, v179
	s_nop 0
	v_mov_b32_e32 v108, v180
	v_mov_b32_e32 v109, v181
	v_mov_b32_e32 v110, v182
	v_mov_b32_e32 v111, v183
	v_mbcnt_lo_u32_b32 v128, -1, 0
	v_mbcnt_hi_u32_b32 v128, -1, v128
	v_mov_b32_e32 v145, v106
	v_mov_b32_e32 v147, v107
	s_nop 0
	v_permlane16_swap_b32_e32 v104, v145
	v_permlane16_swap_b32_e32 v105, v147
	v_permlane16_swap_b32_e32 v108, v110
	v_permlane16_swap_b32_e32 v109, v111
	v_lshlrev_b32_e32 v106, 16, v104
	v_and_b32_e32 v107, 0xffff0000, v104
	v_lshlrev_b32_e32 v144, 16, v145
	v_and_b32_e32 v145, 0xffff0000, v145
	v_lshlrev_b32_e32 v104, 16, v105
	v_and_b32_e32 v105, 0xffff0000, v105
	v_lshlrev_b32_e32 v146, 16, v147
	v_and_b32_e32 v147, 0xffff0000, v147
	v_lshlrev_b32_e32 v148, 16, v108
	v_and_b32_e32 v149, 0xffff0000, v108
	v_lshlrev_b32_e32 v152, 16, v110
	v_and_b32_e32 v153, 0xffff0000, v110
	v_lshlrev_b32_e32 v154, 16, v111
	v_and_b32_e32 v155, 0xffff0000, v111
	v_pk_add_f32 v[110:111], v[80:81], v[106:107]
	v_pk_add_f32 v[106:107], v[84:85], v[144:145]
	v_lshlrev_b32_e32 v150, 16, v109
	v_and_b32_e32 v151, 0xffff0000, v109
	v_pk_add_f32 v[108:109], v[82:83], v[104:105]
	v_pk_add_f32 v[104:105], v[86:87], v[146:147]
	v_pk_add_f32 v[86:87], v[88:89], v[148:149]
	v_mul_f32_e32 v88, v111, v111
	v_mul_f32_e32 v89, v107, v107
	v_pk_add_f32 v[84:85], v[90:91], v[150:151]
	v_pk_add_f32 v[82:83], v[92:93], v[152:153]
	v_mul_f32_e32 v90, v87, v87
	v_fmac_f32_e32 v88, v110, v110
	v_fmac_f32_e32 v89, v106, v106
	v_mul_f32_e32 v91, v83, v83
	v_fmac_f32_e32 v90, v86, v86
	v_fmac_f32_e32 v88, v108, v108
	v_fmac_f32_e32 v89, v104, v104
	v_pk_add_f32 v[80:81], v[94:95], v[154:155]
	v_fmac_f32_e32 v91, v82, v82
	v_fmac_f32_e32 v90, v84, v84
	v_fmac_f32_e32 v88, v109, v109
	v_fmac_f32_e32 v89, v105, v105
	v_fmac_f32_e32 v91, v80, v80
	v_fmac_f32_e32 v90, v85, v85
	v_add_f32_e32 v88, v88, v89
	v_lshlrev_b32_e32 v128, 2, v128
	v_fmac_f32_e32 v91, v81, v81
	v_add_f32_e32 v88, v88, v90
	v_xor_b32_e32 v128, 64, v128
	v_add_f32_e32 v88, v91, v88
	ds_bpermute_b32 v89, v128, v88
	v_mbcnt_lo_u32_b32 v90, -1, 0
	v_mbcnt_hi_u32_b32 v90, -1, v90
	s_waitcnt lgkmcnt(0)
	v_add_f32_e32 v88, v88, v89
	v_lshlrev_b32_e32 v90, 2, v90
	v_xor_b32_e32 v89, 0x80, v90
	ds_bpermute_b32 v89, v89, v88
	s_and_saveexec_b64 s[4:5], vcc
	s_cbranch_execz .LBB0_1151
	s_waitcnt lgkmcnt(0)
	v_add_f32_e32 v88, v88, v89
	v_lshl_add_u32 v89, v143, 4, s77
	ds_write_b32 v89, v88
; __device__ __forceinline__ f32x4 unpack4(u32x2 w) { return (f32x4){bflo(w.x), bfhi(w.x), bflo(w.y), bfhi(w.y)}; }
; __device__ __forceinline__ int lane_fresh() { int l; asm volatile("v_mbcnt_lo_u32_b32 %0, -1, 0\n\tv_mbcnt_hi_u32_b32 %0, -1, %0" : "=v"(l)); return l; }
; __device__ __forceinline__ float shfl_xor_f(float v, int mask) { const int l = lane_fresh(); return __int_as_float(__builtin_amdgcn_ds_bpermute((l ^ mask) << 2, __float_as_int(v))); }
; __device__ __forceinline__ void load_pair16(const u16* rowp32, int fq, u32x2& a, u32x2& b) {
;   const u32x4 w = *(const u32x4*)(rowp32 + ((fq & 1) * 16 + (fq >> 1) * 8));
;   auto rx = __builtin_amdgcn_permlane16_swap(w.x, w.z, false, false);
;   auto ry = __builtin_amdgcn_permlane16_swap(w.y, w.w, false, false);
;   a = (u32x2){rx[0], ry[0]}; b = (u32x2){rx[1], ry[1]};
; }
; __device__ __forceinline__ void phaseG(const Params& p, const int wv, const int rep, unsigned* bar, const bool fused) {
;     ...
;         const int lane_e = lane_fresh(), fr = lane_e & 15, fq = lane_e >> 4;
; #pragma unroll
;         for (int ai = 0; ai < 2; ++ai)
; #pragma unroll
;           for (int m = 0; m < 4; ++m) {
;             const int rrow = ai * 128 + wr * 64 + m * 16 + fr;
;             float ss = 0.f;
; #pragma unroll
;             for (int bj = 0; bj < 2; ++bj) {
;               u32x2 hp[2];
;               load_pair16(H2 + (size_t)(brow + rrow) * 1024 + bcol + bj * 128 + wc * 32, fq, hp[0], hp[1]);
; #pragma unroll
;               for (int n = 0; n < 2; ++n) {
;                 f32x4 v = acc[ai][bj][m][n] + unpack4(hp[n]);
;                 acc[ai][bj][m][n] = v;
;                 ss += v[0] * v[0] + v[1] * v[1] + v[2] * v[2] + v[3] * v[3];
;               }
;             }
;             ss += shfl_xor_f(ss, 16); ss += shfl_xor_f(ss, 32);
;             if (fq == 0) red[rrow * 4 + wc] = ss;
;           }
.LBB0_1151:
	s_or_b64 exec, exec, s[4:5]
	v_or_b32_e32 v143, 48, v142
	v_add_u32_e32 v128, s87, v143
	s_waitcnt lgkmcnt(0)
	v_lshlrev_b64 v[88:89], 11, v[128:129]
	v_lshl_add_u64 v[92:93], v[138:139], 0, v[88:89]
	s_waitcnt vmcnt(8)
	v_mov_b32_e32 v88, v184
	v_mov_b32_e32 v89, v185
	v_mov_b32_e32 v90, v186
	v_mov_b32_e32 v91, v187
	s_nop 0
	v_mov_b32_e32 v92, v188
	v_mov_b32_e32 v93, v189
	v_mov_b32_e32 v94, v190
	v_mov_b32_e32 v95, v191
	v_mbcnt_lo_u32_b32 v128, -1, 0
	v_mbcnt_hi_u32_b32 v128, -1, v128
	v_mov_b32_e32 v145, v90
	v_mov_b32_e32 v147, v91
	s_nop 0
	v_permlane16_swap_b32_e32 v88, v145
	v_permlane16_swap_b32_e32 v89, v147
	v_permlane16_swap_b32_e32 v92, v94
	v_permlane16_swap_b32_e32 v93, v95
	v_lshlrev_b32_e32 v90, 16, v88
	v_and_b32_e32 v91, 0xffff0000, v88
	v_lshlrev_b32_e32 v144, 16, v145
	v_and_b32_e32 v145, 0xffff0000, v145
	v_lshlrev_b32_e32 v88, 16, v89
	v_and_b32_e32 v89, 0xffff0000, v89
	v_lshlrev_b32_e32 v146, 16, v147
	v_and_b32_e32 v147, 0xffff0000, v147
	v_lshlrev_b32_e32 v148, 16, v92
	v_and_b32_e32 v149, 0xffff0000, v92
	v_lshlrev_b32_e32 v152, 16, v94
	v_and_b32_e32 v153, 0xffff0000, v94
	v_lshlrev_b32_e32 v154, 16, v95
	v_and_b32_e32 v155, 0xffff0000, v95
	v_pk_add_f32 v[94:95], v[64:65], v[90:91]
	v_pk_add_f32 v[90:91], v[68:69], v[144:145]
	v_lshlrev_b32_e32 v150, 16, v93
	v_and_b32_e32 v151, 0xffff0000, v93
	v_pk_add_f32 v[92:93], v[66:67], v[88:89]
	v_pk_add_f32 v[88:89], v[70:71], v[146:147]
	v_pk_add_f32 v[70:71], v[72:73], v[148:149]
	v_mul_f32_e32 v72, v95, v95
	v_mul_f32_e32 v73, v91, v91
	v_pk_add_f32 v[68:69], v[74:75], v[150:151]
	v_pk_add_f32 v[66:67], v[76:77], v[152:153]
	v_mul_f32_e32 v74, v71, v71
	v_fmac_f32_e32 v72, v94, v94
	v_fmac_f32_e32 v73, v90, v90
	v_mul_f32_e32 v75, v67, v67
	v_fmac_f32_e32 v74, v70, v70
	v_fmac_f32_e32 v72, v92, v92
	v_fmac_f32_e32 v73, v88, v88
	v_pk_add_f32 v[64:65], v[78:79], v[154:155]
	v_fmac_f32_e32 v75, v66, v66
	v_fmac_f32_e32 v74, v68, v68
	v_fmac_f32_e32 v72, v93, v93
	v_fmac_f32_e32 v73, v89, v89
	v_fmac_f32_e32 v75, v64, v64
	v_fmac_f32_e32 v74, v69, v69
	v_add_f32_e32 v72, v72, v73
	v_lshlrev_b32_e32 v128, 2, v128
	v_fmac_f32_e32 v75, v65, v65
	v_add_f32_e32 v72, v72, v74
	v_xor_b32_e32 v128, 64, v128
	v_add_f32_e32 v72, v75, v72
	ds_bpermute_b32 v73, v128, v72
	v_mbcnt_lo_u32_b32 v74, -1, 0
	v_mbcnt_hi_u32_b32 v74, -1, v74
	s_waitcnt lgkmcnt(0)
	v_add_f32_e32 v72, v72, v73
	v_lshlrev_b32_e32 v74, 2, v74
	v_xor_b32_e32 v73, 0x80, v74
	ds_bpermute_b32 v73, v73, v72
	s_and_saveexec_b64 s[4:5], vcc
	s_cbranch_execz .LBB0_1153
	s_waitcnt lgkmcnt(0)
	v_add_f32_e32 v72, v72, v73
	v_lshl_add_u32 v73, v143, 4, s77
	ds_write_b32 v73, v72
.LBB0_1153:
	s_or_b64 exec, exec, s[4:5]
	v_add_u32_e32 v143, 0x80, v142
	v_add_u32_e32 v128, s87, v143
	s_waitcnt lgkmcnt(0)
	v_lshlrev_b64 v[72:73], 11, v[128:129]
	v_lshl_add_u64 v[76:77], v[138:139], 0, v[72:73]
	s_waitcnt vmcnt(6)
	v_mov_b32_e32 v72, v192
	v_mov_b32_e32 v73, v193
	v_mov_b32_e32 v74, v194
	v_mov_b32_e32 v75, v195
	s_nop 0
	v_mov_b32_e32 v76, v196
	v_mov_b32_e32 v77, v197
	v_mov_b32_e32 v78, v198
	v_mov_b32_e32 v79, v199
	v_mbcnt_lo_u32_b32 v128, -1, 0
	v_mbcnt_hi_u32_b32 v128, -1, v128
	v_mov_b32_e32 v145, v74
	v_mov_b32_e32 v147, v75
	s_nop 0
	v_permlane16_swap_b32_e32 v72, v145
	v_permlane16_swap_b32_e32 v73, v147
	v_permlane16_swap_b32_e32 v76, v78
	v_permlane16_swap_b32_e32 v77, v79
	v_lshlrev_b32_e32 v74, 16, v72
	v_and_b32_e32 v75, 0xffff0000, v72
	v_lshlrev_b32_e32 v144, 16, v145
	v_and_b32_e32 v145, 0xffff0000, v145
	v_lshlrev_b32_e32 v72, 16, v73
	v_and_b32_e32 v73, 0xffff0000, v73
	v_lshlrev_b32_e32 v146, 16, v147
	v_and_b32_e32 v147, 0xffff0000, v147
	v_lshlrev_b32_e32 v148, 16, v76
	v_and_b32_e32 v149, 0xffff0000, v76
	v_lshlrev_b32_e32 v152, 16, v78
	v_and_b32_e32 v153, 0xffff0000, v78
	v_lshlrev_b32_e32 v154, 16, v79
	v_and_b32_e32 v155, 0xffff0000, v79
	v_pk_add_f32 v[78:79], v[48:49], v[74:75]
	v_pk_add_f32 v[74:75], v[52:53], v[144:145]
	v_lshlrev_b32_e32 v150, 16, v77
	v_and_b32_e32 v151, 0xffff0000, v77
	v_pk_add_f32 v[76:77], v[50:51], v[72:73]
	v_pk_add_f32 v[72:73], v[54:55], v[146:147]
	v_pk_add_f32 v[54:55], v[56:57], v[148:149]
	v_mul_f32_e32 v56, v79, v79
	v_mul_f32_e32 v57, v75, v75
	v_pk_add_f32 v[52:53], v[58:59], v[150:151]
	v_pk_add_f32 v[50:51], v[60:61], v[152:153]
	v_mul_f32_e32 v58, v55, v55
	v_fmac_f32_e32 v56, v78, v78
	v_fmac_f32_e32 v57, v74, v74
	v_mul_f32_e32 v59, v51, v51
	v_fmac_f32_e32 v58, v54, v54
	v_fmac_f32_e32 v56, v76, v76
	v_fmac_f32_e32 v57, v72, v72
	v_pk_add_f32 v[48:49], v[62:63], v[154:155]
	v_fmac_f32_e32 v59, v50, v50
	v_fmac_f32_e32 v58, v52, v52
	v_fmac_f32_e32 v56, v77, v77
	v_fmac_f32_e32 v57, v73, v73
	v_fmac_f32_e32 v59, v48, v48
	v_fmac_f32_e32 v58, v53, v53
	v_add_f32_e32 v56, v56, v57
	v_lshlrev_b32_e32 v128, 2, v128
	v_fmac_f32_e32 v59, v49, v49
	v_add_f32_e32 v56, v56, v58
	v_xor_b32_e32 v128, 64, v128
	v_add_f32_e32 v56, v59, v56
	ds_bpermute_b32 v57, v128, v56
	v_mbcnt_lo_u32_b32 v58, -1, 0
	v_mbcnt_hi_u32_b32 v58, -1, v58
	s_waitcnt lgkmcnt(0)
	v_add_f32_e32 v56, v56, v57
	v_lshlrev_b32_e32 v58, 2, v58
	v_xor_b32_e32 v57, 0x80, v58
	ds_bpermute_b32 v57, v57, v56
	s_and_saveexec_b64 s[4:5], vcc
	s_cbranch_execz .LBB0_1155
	s_waitcnt lgkmcnt(0)
	v_add_f32_e32 v56, v56, v57
	v_lshl_add_u32 v57, v143, 4, s77
	ds_write_b32 v57, v56
; __device__ __forceinline__ f32x4 unpack4(u32x2 w) { return (f32x4){bflo(w.x), bfhi(w.x), bflo(w.y), bfhi(w.y)}; }
; __device__ __forceinline__ int lane_fresh() { int l; asm volatile("v_mbcnt_lo_u32_b32 %0, -1, 0\n\tv_mbcnt_hi_u32_b32 %0, -1, %0" : "=v"(l)); return l; }
; __device__ __forceinline__ float shfl_xor_f(float v, int mask) { const int l = lane_fresh(); return __int_as_float(__builtin_amdgcn_ds_bpermute((l ^ mask) << 2, __float_as_int(v))); }
; __device__ __forceinline__ void load_pair16(const u16* rowp32, int fq, u32x2& a, u32x2& b) {
;   const u32x4 w = *(const u32x4*)(rowp32 + ((fq & 1) * 16 + (fq >> 1) * 8));
;   auto rx = __builtin_amdgcn_permlane16_swap(w.x, w.z, false, false);
;   auto ry = __builtin_amdgcn_permlane16_swap(w.y, w.w, false, false);
;   a = (u32x2){rx[0], ry[0]}; b = (u32x2){rx[1], ry[1]};
; }
; __device__ __forceinline__ void phaseG(const Params& p, const int wv, const int rep, unsigned* bar, const bool fused) {
;     ...
;         const int lane_e = lane_fresh(), fr = lane_e & 15, fq = lane_e >> 4;
; #pragma unroll
;         for (int ai = 0; ai < 2; ++ai)
; #pragma unroll
;           for (int m = 0; m < 4; ++m) {
;             const int rrow = ai * 128 + wr * 64 + m * 16 + fr;
;             float ss = 0.f;
; #pragma unroll
;             for (int bj = 0; bj < 2; ++bj) {
;               u32x2 hp[2];
;               load_pair16(H2 + (size_t)(brow + rrow) * 1024 + bcol + bj * 128 + wc * 32, fq, hp[0], hp[1]);
; #pragma unroll
;               for (int n = 0; n < 2; ++n) {
;                 f32x4 v = acc[ai][bj][m][n] + unpack4(hp[n]);
;                 acc[ai][bj][m][n] = v;
;                 ss += v[0] * v[0] + v[1] * v[1] + v[2] * v[2] + v[3] * v[3];
;               }
;             }
;             ss += shfl_xor_f(ss, 16); ss += shfl_xor_f(ss, 32);
;             if (fq == 0) red[rrow * 4 + wc] = ss;
;           }
.LBB0_1155:
	s_or_b64 exec, exec, s[4:5]
	v_add_u32_e32 v143, 0x90, v142
	v_add_u32_e32 v128, s87, v143
	s_waitcnt lgkmcnt(0)
	v_lshlrev_b64 v[56:57], 11, v[128:129]
	v_lshl_add_u64 v[60:61], v[138:139], 0, v[56:57]
	s_waitcnt vmcnt(4)
	v_mov_b32_e32 v56, v200
	v_mov_b32_e32 v57, v201
	v_mov_b32_e32 v58, v202
	v_mov_b32_e32 v59, v203
	s_nop 0
	v_mov_b32_e32 v60, v204
	v_mov_b32_e32 v61, v205
	v_mov_b32_e32 v62, v206
	v_mov_b32_e32 v63, v207
	v_mbcnt_lo_u32_b32 v128, -1, 0
	v_mbcnt_hi_u32_b32 v128, -1, v128
	v_mov_b32_e32 v145, v58
	v_mov_b32_e32 v147, v59
	s_nop 0
	v_permlane16_swap_b32_e32 v56, v145
	v_permlane16_swap_b32_e32 v57, v147
	v_permlane16_swap_b32_e32 v60, v62
	v_permlane16_swap_b32_e32 v61, v63
	v_lshlrev_b32_e32 v58, 16, v56
	v_and_b32_e32 v59, 0xffff0000, v56
	v_lshlrev_b32_e32 v144, 16, v145
	v_and_b32_e32 v145, 0xffff0000, v145
	v_lshlrev_b32_e32 v56, 16, v57
	v_and_b32_e32 v57, 0xffff0000, v57
	v_lshlrev_b32_e32 v146, 16, v147
	v_and_b32_e32 v147, 0xffff0000, v147
	v_lshlrev_b32_e32 v148, 16, v60
	v_and_b32_e32 v149, 0xffff0000, v60
	v_lshlrev_b32_e32 v152, 16, v62
	v_and_b32_e32 v153, 0xffff0000, v62
	v_lshlrev_b32_e32 v154, 16, v63
	v_and_b32_e32 v155, 0xffff0000, v63
	v_pk_add_f32 v[62:63], v[32:33], v[58:59]
	v_pk_add_f32 v[58:59], v[36:37], v[144:145]
	v_lshlrev_b32_e32 v150, 16, v61
	v_and_b32_e32 v151, 0xffff0000, v61
	v_pk_add_f32 v[60:61], v[34:35], v[56:57]
	v_pk_add_f32 v[56:57], v[38:39], v[146:147]
	v_pk_add_f32 v[38:39], v[40:41], v[148:149]
	v_mul_f32_e32 v40, v63, v63
	v_mul_f32_e32 v41, v59, v59
	v_pk_add_f32 v[36:37], v[42:43], v[150:151]
	v_pk_add_f32 v[34:35], v[44:45], v[152:153]
	v_mul_f32_e32 v42, v39, v39
	v_fmac_f32_e32 v40, v62, v62
	v_fmac_f32_e32 v41, v58, v58
	v_mul_f32_e32 v43, v35, v35
	v_fmac_f32_e32 v42, v38, v38
	v_fmac_f32_e32 v40, v60, v60
	v_fmac_f32_e32 v41, v56, v56
	v_pk_add_f32 v[32:33], v[46:47], v[154:155]
	v_fmac_f32_e32 v43, v34, v34
	v_fmac_f32_e32 v42, v36, v36
	v_fmac_f32_e32 v40, v61, v61
	v_fmac_f32_e32 v41, v57, v57
	v_fmac_f32_e32 v43, v32, v32
	v_fmac_f32_e32 v42, v37, v37
	v_add_f32_e32 v40, v40, v41
	v_lshlrev_b32_e32 v128, 2, v128
	v_fmac_f32_e32 v43, v33, v33
	v_add_f32_e32 v40, v40, v42
	v_xor_b32_e32 v128, 64, v128
	v_add_f32_e32 v40, v43, v40
	ds_bpermute_b32 v41, v128, v40
	v_mbcnt_lo_u32_b32 v42, -1, 0
	v_mbcnt_hi_u32_b32 v42, -1, v42
	s_waitcnt lgkmcnt(0)
	v_add_f32_e32 v40, v40, v41
	v_lshlrev_b32_e32 v42, 2, v42
	v_xor_b32_e32 v41, 0x80, v42
	ds_bpermute_b32 v41, v41, v40
	s_and_saveexec_b64 s[4:5], vcc
	s_cbranch_execz .LBB0_1157
	s_waitcnt lgkmcnt(0)
	v_add_f32_e32 v40, v40, v41
	v_lshl_add_u32 v41, v143, 4, s77
	ds_write_b32 v41, v40
; __device__ __forceinline__ f32x4 unpack4(u32x2 w) { return (f32x4){bflo(w.x), bfhi(w.x), bflo(w.y), bfhi(w.y)}; }
; __device__ __forceinline__ int lane_fresh() { int l; asm volatile("v_mbcnt_lo_u32_b32 %0, -1, 0\n\tv_mbcnt_hi_u32_b32 %0, -1, %0" : "=v"(l)); return l; }
; __device__ __forceinline__ float shfl_xor_f(float v, int mask) { const int l = lane_fresh(); return __int_as_float(__builtin_amdgcn_ds_bpermute((l ^ mask) << 2, __float_as_int(v))); }
; __device__ __forceinline__ void load_pair16(const u16* rowp32, int fq, u32x2& a, u32x2& b) {
;   const u32x4 w = *(const u32x4*)(rowp32 + ((fq & 1) * 16 + (fq >> 1) * 8));
;   auto rx = __builtin_amdgcn_permlane16_swap(w.x, w.z, false, false);
;   auto ry = __builtin_amdgcn_permlane16_swap(w.y, w.w, false, false);
;   a = (u32x2){rx[0], ry[0]}; b = (u32x2){rx[1], ry[1]};
; }
; __device__ __forceinline__ void phaseG(const Params& p, const int wv, const int rep, unsigned* bar, const bool fused) {
;     ...
;         const int lane_e = lane_fresh(), fr = lane_e & 15, fq = lane_e >> 4;
; #pragma unroll
;         for (int ai = 0; ai < 2; ++ai)
; #pragma unroll
;           for (int m = 0; m < 4; ++m) {
;             const int rrow = ai * 128 + wr * 64 + m * 16 + fr;
;             float ss = 0.f;
; #pragma unroll
;             for (int bj = 0; bj < 2; ++bj) {
;               u32x2 hp[2];
;               load_pair16(H2 + (size_t)(brow + rrow) * 1024 + bcol + bj * 128 + wc * 32, fq, hp[0], hp[1]);
; #pragma unroll
;               for (int n = 0; n < 2; ++n) {
;                 f32x4 v = acc[ai][bj][m][n] + unpack4(hp[n]);
;                 acc[ai][bj][m][n] = v;
;                 ss += v[0] * v[0] + v[1] * v[1] + v[2] * v[2] + v[3] * v[3];
;               }
;             }
;             ss += shfl_xor_f(ss, 16); ss += shfl_xor_f(ss, 32);
;             if (fq == 0) red[rrow * 4 + wc] = ss;
;           }
.LBB0_1157:
	s_or_b64 exec, exec, s[4:5]
	v_add_u32_e32 v143, 0xa0, v142
	v_add_u32_e32 v128, s87, v143
	s_waitcnt lgkmcnt(0)
	v_lshlrev_b64 v[40:41], 11, v[128:129]
	v_lshl_add_u64 v[44:45], v[138:139], 0, v[40:41]
	s_waitcnt vmcnt(2)
	v_mov_b32_e32 v40, v208
	v_mov_b32_e32 v41, v209
	v_mov_b32_e32 v42, v210
	v_mov_b32_e32 v43, v211
	s_nop 0
	v_mov_b32_e32 v44, v212
	v_mov_b32_e32 v45, v213
	v_mov_b32_e32 v46, v214
	v_mov_b32_e32 v47, v215
	v_mbcnt_lo_u32_b32 v128, -1, 0
	v_mbcnt_hi_u32_b32 v128, -1, v128
	v_mov_b32_e32 v145, v42
	v_mov_b32_e32 v147, v43
	s_nop 0
	v_permlane16_swap_b32_e32 v40, v145
	v_permlane16_swap_b32_e32 v41, v147
	v_permlane16_swap_b32_e32 v44, v46
	v_permlane16_swap_b32_e32 v45, v47
	v_lshlrev_b32_e32 v42, 16, v40
	v_and_b32_e32 v43, 0xffff0000, v40
	v_lshlrev_b32_e32 v144, 16, v145
	v_and_b32_e32 v145, 0xffff0000, v145
	v_lshlrev_b32_e32 v40, 16, v41
	v_and_b32_e32 v41, 0xffff0000, v41
	v_lshlrev_b32_e32 v146, 16, v147
	v_and_b32_e32 v147, 0xffff0000, v147
	v_lshlrev_b32_e32 v148, 16, v44
	v_and_b32_e32 v149, 0xffff0000, v44
	v_lshlrev_b32_e32 v152, 16, v46
	v_and_b32_e32 v153, 0xffff0000, v46
	v_lshlrev_b32_e32 v154, 16, v47
	v_and_b32_e32 v155, 0xffff0000, v47
	v_pk_add_f32 v[46:47], v[16:17], v[42:43]
	v_pk_add_f32 v[42:43], v[20:21], v[144:145]
	v_lshlrev_b32_e32 v150, 16, v45
	v_and_b32_e32 v151, 0xffff0000, v45
	v_pk_add_f32 v[44:45], v[18:19], v[40:41]
	v_pk_add_f32 v[40:41], v[22:23], v[146:147]
	v_pk_add_f32 v[22:23], v[24:25], v[148:149]
	v_mul_f32_e32 v24, v47, v47
	v_mul_f32_e32 v25, v43, v43
	v_pk_add_f32 v[20:21], v[26:27], v[150:151]
	v_pk_add_f32 v[18:19], v[28:29], v[152:153]
	v_mul_f32_e32 v26, v23, v23
	v_fmac_f32_e32 v24, v46, v46
	v_fmac_f32_e32 v25, v42, v42
	v_mul_f32_e32 v27, v19, v19
	v_fmac_f32_e32 v26, v22, v22
	v_fmac_f32_e32 v24, v44, v44
	v_fmac_f32_e32 v25, v40, v40
	v_pk_add_f32 v[16:17], v[30:31], v[154:155]
	v_fmac_f32_e32 v27, v18, v18
	v_fmac_f32_e32 v26, v20, v20
	v_fmac_f32_e32 v24, v45, v45
	v_fmac_f32_e32 v25, v41, v41
	v_fmac_f32_e32 v27, v16, v16
	v_fmac_f32_e32 v26, v21, v21
	v_add_f32_e32 v24, v24, v25
	v_lshlrev_b32_e32 v128, 2, v128
	v_fmac_f32_e32 v27, v17, v17
	v_add_f32_e32 v24, v24, v26
	v_xor_b32_e32 v128, 64, v128
	v_add_f32_e32 v24, v27, v24
	ds_bpermute_b32 v25, v128, v24
	v_mbcnt_lo_u32_b32 v26, -1, 0
	v_mbcnt_hi_u32_b32 v26, -1, v26
	s_waitcnt lgkmcnt(0)
	v_add_f32_e32 v24, v24, v25
	v_lshlrev_b32_e32 v26, 2, v26
	v_xor_b32_e32 v25, 0x80, v26
	ds_bpermute_b32 v25, v25, v24
	s_and_saveexec_b64 s[4:5], vcc
	s_cbranch_execz .LBB0_1159
	s_waitcnt lgkmcnt(0)
	v_add_f32_e32 v24, v24, v25
	v_lshl_add_u32 v25, v143, 4, s77
	ds_write_b32 v25, v24
.LBB0_1159:
	s_or_b64 exec, exec, s[4:5]
	v_add_u32_e32 v142, 0xb0, v142
	v_add_u32_e32 v128, s87, v142
	s_waitcnt lgkmcnt(0)
	v_lshlrev_b64 v[24:25], 11, v[128:129]
	v_lshl_add_u64 v[28:29], v[138:139], 0, v[24:25]
	s_waitcnt vmcnt(0)
	v_mov_b32_e32 v24, v216
	v_mov_b32_e32 v25, v217
	v_mov_b32_e32 v26, v218
	v_mov_b32_e32 v27, v219
	s_nop 0
	v_mov_b32_e32 v28, v220
	v_mov_b32_e32 v29, v221
	v_mov_b32_e32 v30, v222
	v_mov_b32_e32 v31, v223
	v_mbcnt_lo_u32_b32 v128, -1, 0
	v_mbcnt_hi_u32_b32 v128, -1, v128
	v_mov_b32_e32 v139, v26
	v_mov_b32_e32 v143, v27
	s_nop 0
	v_permlane16_swap_b32_e32 v24, v139
	v_permlane16_swap_b32_e32 v25, v143
	v_permlane16_swap_b32_e32 v28, v30
	v_permlane16_swap_b32_e32 v29, v31
	v_lshlrev_b32_e32 v26, 16, v24
	v_and_b32_e32 v27, 0xffff0000, v24
	v_lshlrev_b32_e32 v138, 16, v139
	v_and_b32_e32 v139, 0xffff0000, v139
	v_lshlrev_b32_e32 v24, 16, v25
	v_and_b32_e32 v25, 0xffff0000, v25
	v_lshlrev_b32_e32 v144, 16, v143
	v_and_b32_e32 v145, 0xffff0000, v143
	v_lshlrev_b32_e32 v146, 16, v28
	v_and_b32_e32 v147, 0xffff0000, v28
	v_lshlrev_b32_e32 v150, 16, v30
	v_and_b32_e32 v151, 0xffff0000, v30
	v_lshlrev_b32_e32 v152, 16, v31
	v_and_b32_e32 v153, 0xffff0000, v31
	v_pk_add_f32 v[30:31], v[0:1], v[26:27]
	v_pk_add_f32 v[26:27], v[4:5], v[138:139]
	v_lshlrev_b32_e32 v148, 16, v29
	v_and_b32_e32 v149, 0xffff0000, v29
	v_pk_add_f32 v[28:29], v[2:3], v[24:25]
	v_pk_add_f32 v[24:25], v[6:7], v[144:145]
	v_pk_add_f32 v[6:7], v[8:9], v[146:147]
	v_mul_f32_e32 v8, v31, v31
	v_mul_f32_e32 v9, v27, v27
	v_pk_add_f32 v[4:5], v[10:11], v[148:149]
	v_pk_add_f32 v[2:3], v[12:13], v[150:151]
	v_mul_f32_e32 v10, v7, v7
	v_fmac_f32_e32 v8, v30, v30
	v_fmac_f32_e32 v9, v26, v26
	v_mul_f32_e32 v11, v3, v3
	v_fmac_f32_e32 v10, v6, v6
	v_fmac_f32_e32 v8, v28, v28
	v_fmac_f32_e32 v9, v24, v24
	v_pk_add_f32 v[0:1], v[14:15], v[152:153]
	v_fmac_f32_e32 v11, v2, v2
	v_fmac_f32_e32 v10, v4, v4
	v_fmac_f32_e32 v8, v29, v29
	v_fmac_f32_e32 v9, v25, v25
	v_fmac_f32_e32 v11, v0, v0
	v_fmac_f32_e32 v10, v5, v5
	v_add_f32_e32 v8, v8, v9
	v_lshlrev_b32_e32 v128, 2, v128
	v_fmac_f32_e32 v11, v1, v1
	v_add_f32_e32 v8, v8, v10
	v_xor_b32_e32 v128, 64, v128
	v_add_f32_e32 v8, v11, v8
	ds_bpermute_b32 v9, v128, v8
	v_mbcnt_lo_u32_b32 v10, -1, 0
	v_mbcnt_hi_u32_b32 v10, -1, v10
	s_waitcnt lgkmcnt(0)
	v_add_f32_e32 v8, v8, v9
	v_lshlrev_b32_e32 v10, 2, v10
	v_xor_b32_e32 v9, 0x80, v10
	ds_bpermute_b32 v9, v9, v8
	s_and_saveexec_b64 s[4:5], vcc
	s_cbranch_execz .LBB0_1161
	s_waitcnt lgkmcnt(0)
	v_add_f32_e32 v8, v8, v9
	v_lshl_add_u32 v9, v142, 4, s77
	ds_write_b32 v9, v8
